# prep2 MLA head loop: hoisted invariant loads, next-head prefetch, DPP+permlane wave sums instead of ds_bpermute chains
# speedup vs baseline: 1.0154x; 1.0154x over previous
; DEVI int lbid() { int t = __builtin_amdgcn_workgroup_id_x(); asm volatile("" : "+s"(t)); return t; }
; DEVI unsigned cvt_pk_bf16(float lo, float hi) { unsigned r; asm("v_cvt_pk_bf16_f32 %0, %1, %2" : "=v"(r) : "v"(lo), "v"(hi)); return r; }
; DEVI float bf_lo(unsigned u) { return __uint_as_float(u << 16); }
; DEVI float bf_hi(unsigned u) { return __uint_as_float(u & 0xffff0000u); }
; DEVI float bf2f(bf16_t h) { return __uint_as_float(((unsigned)h) << 16); }
; DEVI bf16_t f2bf(float f) { return (bf16_t)(cvt_pk_bf16(f, 0.f) & 0xffffu); }
; __device__ void phase_prep2(const Params& P, int l, unsigned char* lds) {
;     ...
;   for (int t = lbid() * 8 + wave; t < T; t += gridDim.x * 8) {
;     const int j = lane & 31; const float cs = cosb[t * 32 + j], sn = sinb[t * 32 + j];
;     const unsigned krv = KR[(size_t)t * 64 + lane];
;     for (int h = 0; h < 8; ++h) {
;       const bf16_t* qr = QRAW + (size_t)t * 1536 + h * 192;
;       unsigned u = __builtin_nontemporal_load((const unsigned*)(qr + lane * 2));
;       float a = bf_lo(u), b = bf_hi(u);
;       float ss = wave_sum(a * a + b * b); float rstd = rsqrtf(ss * (1.f / 128.f) + 1e-6f);
;       bf16_t* qo = Q + ((size_t)h * T + t) * 192;
;       *(unsigned*)(qo + lane * 2) = cvt_pk_bf16(a * rstd * qnn[lane * 2] * QS, b * rstd * qnn[lane * 2 + 1] * QS);
;       float xr = bf2f(qr[128 + lane]);
;       float s2 = wave_sum(xr * xr); float y = xr * rsqrtf(s2 * (1.f / 64.f) + 1e-6f) * qnr[lane];
;       float oth = __shfl_xor(y, 32);
;       float o = lane < 32 ? (y * cs - oth * sn) : (oth * sn + y * cs);
;       qo[128 + lane] = f2bf(o * QS);
;       const bf16_t* kr = KVRAW + (size_t)t * 2048 + h * 256;
;       unsigned uk = __builtin_nontemporal_load((const unsigned*)(kr + lane * 2));
;       float ka = bf_lo(uk), kb = bf_hi(uk);
;       float sk = wave_sum(ka * ka + kb * kb); float rk = rsqrtf(sk * (1.f / 128.f) + 1e-6f);
;       bf16_t* ko = Kd + ((size_t)h * T + t) * 192;
;       *(unsigned*)(ko + lane * 2) = cvt_pk_bf16(ka * rk * knn[lane * 2], kb * rk * knn[lane * 2 + 1]);
;       ko[128 + lane] = (bf16_t)krv;
;     }
.LBB0_154:
	v_lshl_or_b32 v18, v2, 5, v28
	v_ashrrev_i32_e32 v19, 31, v18
	v_ashrrev_i32_e32 v3, 31, v2
	v_lshlrev_b64 v[18:19], 2, v[18:19]
	v_lshl_add_u64 v[20:21], s[18:19], 0, v[18:19]
	v_lshlrev_b64 v[22:23], 7, v[2:3]
	v_lshl_add_u64 v[18:19], s[14:15], 0, v[18:19]
	v_lshl_add_u64 v[22:23], v[6:7], 0, v[22:23]
	global_load_dword v35, v[20:21], off
	global_load_dword v36, v[18:19], off
	global_load_ushort v37, v[22:23], off
	v_lshlrev_b64 v[18:19], 12, v[2:3]
	v_mad_i64_i32 v[20:21], s[0:1], v2, s56, 0
	v_mad_i64_i32 v[22:23], s[0:1], v2, s56, v[38:39]
	v_mad_i64_i32 v[24:25], s[0:1], v2, s30, v[14:15]
	v_mad_i64_i32 v[26:27], s[0:1], v2, s30, v[16:17]
	v_lshl_add_u64 v[18:19], v[12:13], 0, v[18:19]
	v_or_b32_e32 v20, v0, v20
	global_load_dword v106, v[8:9], off
	global_load_dwordx2 v[108:109], v[10:11], off
	v_lshl_add_u64 v[110:111], s[24:25], 0, v[26:27]
	global_load_dword v100, v[110:111], off nt
	v_lshl_add_u64 v[110:111], s[24:25], 0, v[24:25]
	global_load_ushort v101, v[110:111], off
	v_lshl_add_u64 v[110:111], s[24:25], 0, v[18:19]
	global_load_dword v102, v[110:111], off nt
	s_waitcnt vmcnt(0)
	s_mov_b32 s0, 8
.LBB0_155:
	v_lshl_add_u64 v[40:41], s[24:25], 0, v[22:23]
	v_add_co_u32_e32 v42, vcc, s34, v40
	s_nop 0
	v_addc_co_u32_e32 v43, vcc, 0, v41, vcc
	s_mov_b32 s1, 0x3015c000
	s_add_i32 s0, s0, -1
	v_lshl_add_u64 v[18:19], v[18:19], 0, s[22:23]
	v_lshl_add_u64 v[22:23], v[22:23], 0, s[44:45]
	v_lshl_add_u64 v[24:25], v[24:25], 0, s[38:39]
	v_lshl_add_u64 v[26:27], v[26:27], 0, s[38:39]
	v_lshl_add_u64 v[110:111], s[24:25], 0, v[26:27]
	global_load_dword v103, v[110:111], off nt
	v_lshl_add_u64 v[110:111], s[24:25], 0, v[24:25]
	global_load_ushort v104, v[110:111], off
	v_lshl_add_u64 v[110:111], s[24:25], 0, v[18:19]
	global_load_dword v105, v[110:111], off nt
	s_cmp_eq_u32 s0, 0
	v_lshlrev_b32_e32 v46, 16, v100
	v_and_b32_e32 v47, 0xffff0000, v100
	v_pk_mul_f32 v[48:49], v[46:47], v[46:47]
	s_nop 0
	v_add_f32_e32 v3, v48, v49
	s_nop 1
	v_add_f32_dpp v3, v3, v3 quad_perm:[1,0,3,2] row_mask:0xf bank_mask:0xf bound_ctrl:1
	s_nop 1
	v_add_f32_dpp v3, v3, v3 quad_perm:[2,3,0,1] row_mask:0xf bank_mask:0xf bound_ctrl:1
	s_nop 1
	v_add_f32_dpp v3, v3, v3 row_half_mirror row_mask:0xf bank_mask:0xf bound_ctrl:1
	s_nop 1
	v_add_f32_dpp v3, v3, v3 row_mirror row_mask:0xf bank_mask:0xf bound_ctrl:1
	v_mov_b32_e32 v48, v3
	s_nop 1
	v_permlane16_swap_b32_e32 v3, v48
	v_add_f32_e32 v48, v3, v48
	v_mov_b32_e32 v3, v48
	s_nop 1
	v_permlane32_swap_b32_e32 v48, v3
	v_add_f32_e32 v3, v48, v3
	v_fmamk_f32 v3, v3, 0x3c000000, v180
	v_mul_f32_e32 v48, 0x4b800000, v3
	v_cmp_gt_f32_e32 vcc, s31, v3
	s_nop 1
	v_cndmask_b32_e32 v3, v3, v48, vcc
	v_rsq_f32_e32 v3, v3
	s_nop 0
	v_mul_f32_e32 v48, 0x45800000, v3
	v_cndmask_b32_e32 v3, v3, v48, vcc
	v_mul_f32_e32 v46, v3, v46
	v_mul_f32_e32 v3, v3, v47
	v_mul_f32_e32 v3, v5, v3
	v_mul_f32_e32 v46, v4, v46
	v_mul_f32_e32 v3, 0x3dd53b94, v3
	v_mul_f32_e32 v46, 0x3dd53b94, v46
	v_cvt_pk_bf16_f32 v3, v46, v3
	global_store_dword v[42:43], v3, off
	s_nop 0
	v_lshl_add_u64 v[42:43], s[24:25], 0, v[20:21]
	v_add_co_u32_e64 v46, s[42:43], s34, v42
	v_add_co_u32_e32 v40, vcc, s1, v40
	s_nop 0
	v_addc_co_u32_e64 v47, s[42:43], 0, v43, s[42:43]
	s_mov_b64 s[42:43], vcc
	v_add_co_u32_e32 v42, vcc, 0x3015c000, v42
	s_nop 0
	v_addc_co_u32_e32 v43, vcc, 0, v43, vcc
	global_store_short v[42:43], v37, off offset:256
	v_lshlrev_b32_e32 v42, 16, v101
	v_mul_f32_e32 v43, v42, v42
	v_lshl_add_u64 v[20:21], v[20:21], 0, s[44:45]
	v_addc_co_u32_e64 v41, s[42:43], 0, v41, s[42:43]
	s_nop 1
	v_add_f32_dpp v43, v43, v43 quad_perm:[1,0,3,2] row_mask:0xf bank_mask:0xf bound_ctrl:1
	s_nop 1
	v_add_f32_dpp v43, v43, v43 quad_perm:[2,3,0,1] row_mask:0xf bank_mask:0xf bound_ctrl:1
	s_nop 1
	v_add_f32_dpp v43, v43, v43 row_half_mirror row_mask:0xf bank_mask:0xf bound_ctrl:1
	s_nop 1
	v_add_f32_dpp v43, v43, v43 row_mirror row_mask:0xf bank_mask:0xf bound_ctrl:1
	v_mov_b32_e32 v49, v43
	s_nop 1
	v_permlane16_swap_b32_e32 v43, v49
	v_add_f32_e32 v49, v43, v49
	v_mov_b32_e32 v43, v49
	s_nop 1
	v_permlane32_swap_b32_e32 v49, v43
	v_add_f32_e32 v43, v49, v43
	v_fmamk_f32 v43, v43, 0x3c800000, v180
	v_mul_f32_e32 v49, 0x4b800000, v43
	v_cmp_gt_f32_e32 vcc, s31, v43
	s_nop 1
	v_cndmask_b32_e32 v43, v43, v49, vcc
	v_rsq_f32_e32 v43, v43
	s_nop 0
	v_mul_f32_e32 v49, 0x45800000, v43
	v_cndmask_b32_e32 v43, v43, v49, vcc
	v_mul_f32_e32 v42, v43, v42
	v_and_b32_e32 v43, 0xffff0000, v102
	v_mul_f32_e32 v50, v106, v42
	v_lshlrev_b32_e32 v42, 16, v102
	v_pk_mul_f32 v[48:49], v[42:43], v[42:43]
	s_nop 0
	v_add_f32_e32 v3, v48, v49
	ds_bpermute_b32 v49, v29, v50
	s_nop 1
	v_add_f32_dpp v3, v3, v3 quad_perm:[1,0,3,2] row_mask:0xf bank_mask:0xf bound_ctrl:1
	s_nop 1
	v_add_f32_dpp v3, v3, v3 quad_perm:[2,3,0,1] row_mask:0xf bank_mask:0xf bound_ctrl:1
	s_nop 1
	v_add_f32_dpp v3, v3, v3 row_half_mirror row_mask:0xf bank_mask:0xf bound_ctrl:1
	s_nop 1
	v_add_f32_dpp v3, v3, v3 row_mirror row_mask:0xf bank_mask:0xf bound_ctrl:1
	v_mov_b32_e32 v48, v3
	s_nop 1
	v_permlane16_swap_b32_e32 v3, v48
	v_add_f32_e32 v48, v3, v48
	v_mov_b32_e32 v3, v48
	s_nop 1
	v_permlane32_swap_b32_e32 v48, v3
	v_add_f32_e32 v3, v48, v3
	s_waitcnt lgkmcnt(0)
	v_mul_f32_e32 v49, v36, v49
	v_cndmask_b32_e64 v49, v49, -v49, s[40:41]
	v_fmac_f32_e32 v49, v35, v50
	v_mul_f32_e32 v49, 0x3dd53b94, v49
	v_cvt_pk_bf16_f32 v49, v49, v1
	global_store_short v[46:47], v49, off offset:256
	v_fmamk_f32 v3, v3, 0x3c000000, v180
	v_mul_f32_e32 v48, 0x4b800000, v3
	v_cmp_gt_f32_e32 vcc, s31, v3
	s_nop 1
	v_cndmask_b32_e32 v3, v3, v48, vcc
	v_rsq_f32_e32 v3, v3
	s_nop 0
	v_mul_f32_e32 v46, 0x45800000, v3
	v_cndmask_b32_e32 v3, v3, v46, vcc
	v_mul_f32_e32 v42, v3, v42
	v_mul_f32_e32 v3, v3, v43
	v_mul_f32_e32 v3, v109, v3
	v_mul_f32_e32 v42, v108, v42
	v_cvt_pk_bf16_f32 v3, v42, v3
	global_store_dword v[40:41], v3, off
	s_waitcnt vmcnt(4)
	v_mov_b32_e32 v100, v103
	v_mov_b32_e32 v101, v104
	v_mov_b32_e32 v102, v105
	s_cbranch_scc0 .LBB0_155
	v_add_u32_e32 v2, s29, v2
	v_cmp_lt_i32_e32 vcc, s87, v2
	s_or_b64 s[26:27], vcc, s[26:27]
	s_andn2_b64 exec, exec, s[26:27]
	s_cbranch_execnz .LBB0_154
